# int8 quantisation phase: xor-1/2/4/8 steps of the wave reductions through DPP instead of ds_bpermute (exact), LDS waits in that phase made full
# baseline (speedup 1.0000x reference)
; #define GAS __attribute__((address_space(1)))
; __device__ __forceinline__ void quant_row(const v4u a, const v4u b, unsigned char* dst, float* sc, bool is_w, int lane) {
;     float v[16];
; #pragma unroll
;     for (int i = 0; i < 4; ++i) { v[2 * i] = __uint_as_float(a[i] << 16); v[2 * i + 1] = __uint_as_float(a[i] & 0xffff0000u); v[8 + 2 * i] = __uint_as_float(b[i] << 16); v[8 + 2 * i + 1] = __uint_as_float(b[i] & 0xffff0000u); }
;     float mx = 0.f, ss = 0.f;
; #pragma unroll
;     for (int i = 0; i < 16; ++i) { mx = fmaxf(mx, fabsf(v[i])); ss += v[i] * v[i]; }
;     mx = wave_max(mx); ss = wave_sum(ss);
;     const float inv = mx > 0.f ? 127.f / mx : 0.f;
;     v4u q;
; #pragma unroll
;     for (int w = 0; w < 4; ++w) q[w] = q8x4((f32x4){v[4 * w], v[4 * w + 1], v[4 * w + 2], v[4 * w + 3]}, inv);
;     *(GAS v4u*)(dst + 16 * lane) = q;
;     if (lane == 0) *sc = is_w ? mx * (1.f / 127.f) : rsqrtf(ss * (1.f / DM) + EPS) * (mx * (1.f / 127.f));
; }
; __device__ __forceinline__ void p_quant(Frame& F) {
;     ...
;     for (int r = first; r < last; r += 4 * step) {
;         v4u a[4], b[4];
; #pragma unroll
;         for (int k = 0; k < 4; ++k) {
;             const int rk = r + k * step < last ? r + k * step : r;
;             const bf16* sp = WSP(bf16, WS_H2B) + (size_t)rk * 1024;
;             a[k] = *(const GAS v4u*)(sp + 16 * l); b[k] = *(const GAS v4u*)(sp + 16 * l + 8);
;         }
; #pragma unroll
;         for (int k = 0; k < 4; ++k) {
;             const int rk = r + k * step; if (rk >= last) break;
;             quant_row(a[k], b[k], WSP(unsigned char, WS_A8) + (size_t)rk * 1024, WSP(float, WS_RS8) + rk, false, l);
.LBB0_2070:
	s_ashr_i32 s15, s14, 31
	s_add_i32 s4, s14, s19
	s_cmp_lt_i32 s4, s18
	s_cselect_b64 s[16:17], -1, 0
	s_and_b64 s[0:1], s[16:17], exec
	s_cselect_b32 s0, s4, s14
	s_ashr_i32 s1, s0, 31
	s_lshl_b64 s[0:1], s[0:1], 11
	s_add_i32 s8, s22, s14
	s_cmp_lt_i32 s8, s18
	s_cselect_b64 s[12:13], -1, 0
	s_and_b64 s[6:7], s[12:13], exec
	s_cselect_b32 s6, s8, s14
	s_ashr_i32 s7, s6, 31
	s_lshl_b64 s[28:29], s[6:7], 11
	s_add_i32 s6, s23, s14
	s_cmp_lt_i32 s6, s18
	s_cselect_b64 s[10:11], -1, 0
	s_and_b64 s[30:31], s[10:11], exec
	s_cselect_b32 s30, s6, s14
	s_lshl_b64 s[34:35], s[14:15], 11
	s_waitcnt vmcnt(4)
	v_lshl_add_u64 v[8:9], v[24:25], 0, s[34:35]
	s_waitcnt lgkmcnt(0)
	global_load_dwordx4 v[0:3], v[8:9], off
	global_load_dwordx4 v[4:7], v[8:9], off offset:16
	s_ashr_i32 s31, s30, 31
	v_lshl_add_u64 v[8:9], v[24:25], 0, s[0:1]
	v_lshl_add_u64 v[36:37], v[24:25], 0, s[28:29]
	s_lshl_b64 s[0:1], s[30:31], 11
	global_load_dwordx4 v[16:19], v[8:9], off offset:16
	global_load_dwordx4 v[20:23], v[8:9], off
	s_nop 0
	global_load_dwordx4 v[8:11], v[36:37], off offset:16
	global_load_dwordx4 v[12:15], v[36:37], off
	v_lshl_add_u64 v[36:37], v[24:25], 0, s[0:1]
	s_lshl_b64 s[0:1], s[14:15], 10
	s_waitcnt vmcnt(5)
	v_lshlrev_b32_e32 v39, 16, v0
	v_and_b32_e32 v40, 0xffff0000, v0
	v_lshlrev_b32_e32 v43, 16, v1
	v_and_b32_e32 v44, 0xffff0000, v1
	v_max3_f32 v0, |v39|, 0, |v40|
	v_lshlrev_b32_e32 v47, 16, v2
	v_and_b32_e32 v48, 0xffff0000, v2
	v_max3_f32 v0, v0, |v43|, |v44|
	v_lshlrev_b32_e32 v51, 16, v3
	v_and_b32_e32 v52, 0xffff0000, v3
	v_max3_f32 v0, v0, |v47|, |v48|
	s_waitcnt vmcnt(4)
	v_lshlrev_b32_e32 v41, 16, v4
	v_and_b32_e32 v42, 0xffff0000, v4
	v_max3_f32 v0, v0, |v51|, |v52|
	v_lshlrev_b32_e32 v45, 16, v5
	v_and_b32_e32 v46, 0xffff0000, v5
	v_max3_f32 v0, v0, |v41|, |v42|
	v_lshlrev_b32_e32 v49, 16, v6
	v_and_b32_e32 v50, 0xffff0000, v6
	v_max3_f32 v0, v0, |v45|, |v46|
	v_lshlrev_b32_e32 v53, 16, v7
	v_and_b32_e32 v54, 0xffff0000, v7
	v_max3_f32 v0, v0, |v49|, |v50|
	v_max3_f32 v0, v0, |v53|, |v54|
	s_nop 1
	v_mov_b32_dpp v1, v0 quad_perm:[1,0,3,2] row_mask:0xf bank_mask:0xf
	v_mul_f32_e32 v38, v40, v40
	v_fmac_f32_e32 v38, v39, v39
	v_fmac_f32_e32 v38, v43, v43
	v_fmac_f32_e32 v38, v44, v44
	s_waitcnt lgkmcnt(0)
	v_max_f32_e32 v1, v1, v1
	v_max_f32_e32 v55, v0, v1
	global_load_dwordx4 v[0:3], v[36:37], off offset:16
	global_load_dwordx4 v[4:7], v[36:37], off
	v_fmac_f32_e32 v38, v47, v47
	v_fmac_f32_e32 v38, v48, v48
	v_fmac_f32_e32 v38, v51, v51
	v_fmac_f32_e32 v38, v52, v52
	v_fmac_f32_e32 v38, v41, v41
	v_fmac_f32_e32 v38, v42, v42
	v_fmac_f32_e32 v38, v45, v45
	v_fmac_f32_e32 v38, v46, v46
	v_fmac_f32_e32 v38, v49, v49
	v_fmac_f32_e32 v38, v50, v50
	v_fmac_f32_e32 v38, v53, v53
	s_nop 1
	v_mov_b32_dpp v56, v55 quad_perm:[2,3,0,1] row_mask:0xf bank_mask:0xf
	v_fmac_f32_e32 v38, v54, v54
	s_nop 1
	v_mov_b32_dpp v57, v38 quad_perm:[1,0,3,2] row_mask:0xf bank_mask:0xf
	s_waitcnt lgkmcnt(0)
	v_max_f32_e32 v36, v56, v56
	v_max_f32_e32 v36, v55, v36
	s_waitcnt lgkmcnt(0)
	v_add_f32_e32 v37, v38, v57
	s_nop 1
	v_mov_b32_dpp v38, v36 row_half_mirror row_mask:0xf bank_mask:0xf
	s_nop 1
	v_mov_b32_dpp v55, v37 quad_perm:[2,3,0,1] row_mask:0xf bank_mask:0xf
	s_waitcnt lgkmcnt(0)
	v_max_f32_e32 v38, v38, v38
	s_waitcnt lgkmcnt(0)
	v_add_f32_e32 v37, v37, v55
	v_max_f32_e32 v36, v36, v38
	s_nop 1
	v_mov_b32_dpp v38, v37 row_half_mirror row_mask:0xf bank_mask:0xf
	s_nop 1
	v_mov_b32_dpp v55, v36 row_mirror row_mask:0xf bank_mask:0xf
	s_waitcnt lgkmcnt(0)
	v_add_f32_e32 v37, v37, v38
	s_waitcnt lgkmcnt(0)
	v_max_f32_e32 v38, v55, v55
	v_max_f32_e32 v36, v36, v38
	ds_bpermute_b32 v38, v32, v36
	s_nop 1
	v_mov_b32_dpp v55, v37 row_mirror row_mask:0xf bank_mask:0xf
	s_waitcnt lgkmcnt(0)
	v_max_f32_e32 v38, v38, v38
	v_max_f32_e32 v36, v36, v38
	ds_bpermute_b32 v38, v33, v36
	s_waitcnt lgkmcnt(0)
	v_add_f32_e32 v37, v37, v55
	ds_bpermute_b32 v55, v32, v37
	s_waitcnt lgkmcnt(0)
	v_max_f32_e32 v38, v38, v38
	v_max_f32_e32 v36, v36, v38
	s_waitcnt lgkmcnt(0)
	v_add_f32_e32 v37, v37, v55
	v_div_scale_f32 v55, s[28:29], v36, v36, s24
	v_rcp_f32_e32 v56, v55
	v_div_scale_f32 v57, vcc, s24, v36, s24
	ds_bpermute_b32 v38, v33, v37
	v_fma_f32 v58, -v55, v56, 1.0
	v_fmac_f32_e32 v56, v58, v56
	v_mul_f32_e32 v58, v57, v56
	v_fma_f32 v59, -v55, v58, v57
	v_fmac_f32_e32 v58, v59, v56
	v_fma_f32 v55, -v55, v58, v57
	v_div_fmas_f32 v55, v55, v56, v58
	v_div_fixup_f32 v55, v55, v36, s24
	v_cmp_lt_f32_e32 vcc, 0, v36
	s_nop 1
	v_cndmask_b32_e32 v55, 0, v55, vcc
	v_fmaak_f32 v39, v39, v55, 0x4b400000
	v_fmaak_f32 v40, v40, v55, 0x4b400000
	v_fmaak_f32 v43, v43, v55, 0x4b400000
	v_fmaak_f32 v44, v44, v55, 0x4b400000
	v_fmaak_f32 v47, v47, v55, 0x4b400000
	v_fmaak_f32 v48, v48, v55, 0x4b400000
	v_fmaak_f32 v51, v51, v55, 0x4b400000
	v_fmaak_f32 v52, v52, v55, 0x4b400000
	v_fmaak_f32 v41, v41, v55, 0x4b400000
	v_fmaak_f32 v42, v42, v55, 0x4b400000
	v_fmaak_f32 v45, v45, v55, 0x4b400000
	v_fmaak_f32 v46, v46, v55, 0x4b400000
	v_fmaak_f32 v49, v49, v55, 0x4b400000
	v_fmaak_f32 v50, v50, v55, 0x4b400000
	v_fmaak_f32 v53, v53, v55, 0x4b400000
	v_fmaak_f32 v54, v54, v55, 0x4b400000
	v_perm_b32 v43, v44, v43, s25
	v_perm_b32 v39, v40, v39, s25
	v_perm_b32 v44, v52, v51, s25
	v_perm_b32 v47, v48, v47, s25
	v_perm_b32 v45, v46, v45, s25
	v_perm_b32 v42, v42, v41, s25
	v_perm_b32 v46, v54, v53, s25
	v_perm_b32 v48, v50, v49, s25
	v_perm_b32 v40, v43, v39, s26
	v_perm_b32 v41, v44, v47, s26
	v_perm_b32 v42, v45, v42, s26
	v_perm_b32 v43, v46, v48, s26
	v_lshl_add_u64 v[44:45], v[26:27], 0, s[0:1]
	global_store_dwordx4 v[44:45], v[40:43], off
	s_and_saveexec_b64 s[0:1], s[2:3]
	s_cbranch_execz .LBB0_2072
	s_waitcnt lgkmcnt(0)
	v_add_f32_e32 v37, v37, v38
	v_fmamk_f32 v37, v37, 0x3a800000, v35
	v_mul_f32_e32 v38, 0x4b800000, v37
	v_cmp_gt_f32_e32 vcc, s27, v37
	s_lshl_b64 s[14:15], s[14:15], 2
	s_add_u32 s14, s20, s14
	v_cndmask_b32_e32 v37, v37, v38, vcc
	v_rsq_f32_e32 v37, v37
	v_mul_f32_e32 v36, 0x3c010204, v36
	s_addc_u32 s15, s21, s15
	v_mul_f32_e32 v38, 0x45800000, v37
	v_cndmask_b32_e32 v37, v37, v38, vcc
	v_mul_f32_e32 v36, v36, v37
	global_store_dword v34, v36, s[14:15]
; #define GAS __attribute__((address_space(1)))
; __device__ __forceinline__ void quant_row(const v4u a, const v4u b, unsigned char* dst, float* sc, bool is_w, int lane) {
;     float v[16];
; #pragma unroll
;     for (int i = 0; i < 4; ++i) { v[2 * i] = __uint_as_float(a[i] << 16); v[2 * i + 1] = __uint_as_float(a[i] & 0xffff0000u); v[8 + 2 * i] = __uint_as_float(b[i] << 16); v[8 + 2 * i + 1] = __uint_as_float(b[i] & 0xffff0000u); }
;     float mx = 0.f, ss = 0.f;
; #pragma unroll
;     for (int i = 0; i < 16; ++i) { mx = fmaxf(mx, fabsf(v[i])); ss += v[i] * v[i]; }
;     mx = wave_max(mx); ss = wave_sum(ss);
;     const float inv = mx > 0.f ? 127.f / mx : 0.f;
;     v4u q;
; #pragma unroll
;     for (int w = 0; w < 4; ++w) q[w] = q8x4((f32x4){v[4 * w], v[4 * w + 1], v[4 * w + 2], v[4 * w + 3]}, inv);
;     *(GAS v4u*)(dst + 16 * lane) = q;
;     if (lane == 0) *sc = is_w ? mx * (1.f / 127.f) : rsqrtf(ss * (1.f / DM) + EPS) * (mx * (1.f / 127.f));
; }
; __device__ __forceinline__ void p_quant(Frame& F) {
;     ...
;     for (int r = first; r < last; r += 4 * step) {
;         v4u a[4], b[4];
; #pragma unroll
;         for (int k = 0; k < 4; ++k) {
;             const int rk = r + k * step < last ? r + k * step : r;
;             const bf16* sp = WSP(bf16, WS_H2B) + (size_t)rk * 1024;
;             a[k] = *(const GAS v4u*)(sp + 16 * l); b[k] = *(const GAS v4u*)(sp + 16 * l + 8);
;         }
; #pragma unroll
;         for (int k = 0; k < 4; ++k) {
;             const int rk = r + k * step; if (rk >= last) break;
;             quant_row(a[k], b[k], WSP(unsigned char, WS_A8) + (size_t)rk * 1024, WSP(float, WS_RS8) + rk, false, l);
.LBB0_2072:
	s_or_b64 exec, exec, s[0:1]
	s_andn2_b64 vcc, exec, s[16:17]
	s_cbranch_vccnz .LBB0_2069
	s_waitcnt vmcnt(5)
	v_lshlrev_b32_e32 v36, 16, v20
	v_and_b32_e32 v20, 0xffff0000, v20
	v_lshlrev_b32_e32 v37, 16, v16
	s_waitcnt lgkmcnt(0)
	v_and_b32_e32 v38, 0xffff0000, v16
	v_lshlrev_b32_e32 v39, 16, v21
	v_and_b32_e32 v21, 0xffff0000, v21
	v_max3_f32 v16, |v36|, 0, |v20|
	v_lshlrev_b32_e32 v42, 16, v22
	v_and_b32_e32 v22, 0xffff0000, v22
	v_max3_f32 v16, v16, |v39|, |v21|
	v_lshlrev_b32_e32 v45, 16, v23
	v_and_b32_e32 v23, 0xffff0000, v23
	v_max3_f32 v16, v16, |v42|, |v22|
	v_max3_f32 v16, v16, |v45|, |v23|
	v_lshlrev_b32_e32 v40, 16, v17
	v_and_b32_e32 v41, 0xffff0000, v17
	v_max3_f32 v16, v16, |v37|, |v38|
	v_lshlrev_b32_e32 v43, 16, v18
	v_and_b32_e32 v44, 0xffff0000, v18
	v_max3_f32 v16, v16, |v40|, |v41|
	v_lshlrev_b32_e32 v46, 16, v19
	v_and_b32_e32 v19, 0xffff0000, v19
	v_max3_f32 v16, v16, |v43|, |v44|
	v_max3_f32 v16, v16, |v46|, |v19|
	s_nop 1
	v_mov_b32_dpp v18, v16 quad_perm:[1,0,3,2] row_mask:0xf bank_mask:0xf
	v_mul_f32_e32 v17, v20, v20
	v_fmac_f32_e32 v17, v36, v36
	v_fmac_f32_e32 v17, v39, v39
	v_fmac_f32_e32 v17, v21, v21
	s_waitcnt lgkmcnt(0)
	v_max_f32_e32 v18, v18, v18
	v_max_f32_e32 v16, v16, v18
	v_fmac_f32_e32 v17, v42, v42
	s_nop 1
	v_mov_b32_dpp v18, v16 quad_perm:[2,3,0,1] row_mask:0xf bank_mask:0xf
	v_fmac_f32_e32 v17, v22, v22
	v_fmac_f32_e32 v17, v45, v45
	v_fmac_f32_e32 v17, v23, v23
	v_fmac_f32_e32 v17, v37, v37
	v_fmac_f32_e32 v17, v38, v38
	s_waitcnt lgkmcnt(0)
	v_max_f32_e32 v18, v18, v18
	v_fmac_f32_e32 v17, v40, v40
	v_max_f32_e32 v16, v16, v18
	v_fmac_f32_e32 v17, v41, v41
	s_nop 1
	v_mov_b32_dpp v18, v16 row_half_mirror row_mask:0xf bank_mask:0xf
	v_fmac_f32_e32 v17, v43, v43
	v_fmac_f32_e32 v17, v44, v44
	v_fmac_f32_e32 v17, v46, v46
	v_fmac_f32_e32 v17, v19, v19
	s_waitcnt lgkmcnt(0)
	v_max_f32_e32 v18, v18, v18
	s_nop 1
	v_mov_b32_dpp v47, v17 quad_perm:[1,0,3,2] row_mask:0xf bank_mask:0xf
	v_max_f32_e32 v16, v16, v18
	s_nop 1
	v_mov_b32_dpp v18, v16 row_mirror row_mask:0xf bank_mask:0xf
	s_ashr_i32 s5, s4, 31
	s_waitcnt lgkmcnt(0)
	v_add_f32_e32 v17, v17, v47
	s_nop 1
	v_mov_b32_dpp v47, v17 quad_perm:[2,3,0,1] row_mask:0xf bank_mask:0xf
	s_waitcnt lgkmcnt(0)
	v_max_f32_e32 v18, v18, v18
	v_max_f32_e32 v16, v16, v18
	ds_bpermute_b32 v18, v32, v16
	s_waitcnt lgkmcnt(0)
	v_add_f32_e32 v17, v17, v47
	s_nop 1
	v_mov_b32_dpp v47, v17 row_half_mirror row_mask:0xf bank_mask:0xf
	s_waitcnt lgkmcnt(0)
	v_max_f32_e32 v18, v18, v18
	v_max_f32_e32 v16, v16, v18
	ds_bpermute_b32 v18, v33, v16
	s_waitcnt lgkmcnt(0)
	v_add_f32_e32 v17, v17, v47
	s_nop 1
	v_mov_b32_dpp v47, v17 row_mirror row_mask:0xf bank_mask:0xf
	s_waitcnt lgkmcnt(0)
	v_max_f32_e32 v18, v18, v18
	v_max_f32_e32 v16, v16, v18
	s_waitcnt lgkmcnt(0)
	v_add_f32_e32 v17, v17, v47
	v_div_scale_f32 v47, s[0:1], v16, v16, s24
	v_rcp_f32_e32 v48, v47
	ds_bpermute_b32 v18, v32, v17
	s_lshl_b64 s[0:1], s[4:5], 10
	v_fma_f32 v49, -v47, v48, 1.0
	v_fmac_f32_e32 v48, v49, v48
	v_div_scale_f32 v49, vcc, s24, v16, s24
	v_mul_f32_e32 v50, v49, v48
	v_fma_f32 v51, -v47, v50, v49
	v_fmac_f32_e32 v50, v51, v48
	v_fma_f32 v47, -v47, v50, v49
	v_div_fmas_f32 v47, v47, v48, v50
	v_div_fixup_f32 v47, v47, v16, s24
	v_cmp_lt_f32_e32 vcc, 0, v16
	s_waitcnt lgkmcnt(0)
	v_add_f32_e32 v17, v17, v18
	ds_bpermute_b32 v18, v33, v17
	v_cndmask_b32_e32 v47, 0, v47, vcc
	v_fmaak_f32 v36, v36, v47, 0x4b400000
	v_fmaak_f32 v20, v20, v47, 0x4b400000
	v_fmaak_f32 v39, v39, v47, 0x4b400000
	v_fmaak_f32 v21, v21, v47, 0x4b400000
	v_perm_b32 v21, v21, v39, s25
	v_perm_b32 v20, v20, v36, s25
	v_perm_b32 v20, v21, v20, s26
	v_fmaak_f32 v21, v42, v47, 0x4b400000
	v_fmaak_f32 v22, v22, v47, 0x4b400000
	v_fmaak_f32 v36, v45, v47, 0x4b400000
	v_fmaak_f32 v23, v23, v47, 0x4b400000
	v_perm_b32 v23, v23, v36, s25
	v_perm_b32 v21, v22, v21, s25
	v_perm_b32 v21, v23, v21, s26
	v_fmaak_f32 v22, v37, v47, 0x4b400000
	v_fmaak_f32 v23, v38, v47, 0x4b400000
	v_fmaak_f32 v36, v40, v47, 0x4b400000
	v_fmaak_f32 v37, v41, v47, 0x4b400000
	v_perm_b32 v36, v37, v36, s25
	v_perm_b32 v22, v23, v22, s25
	v_perm_b32 v22, v36, v22, s26
	v_fmaak_f32 v23, v43, v47, 0x4b400000
	v_fmaak_f32 v36, v44, v47, 0x4b400000
	v_fmaak_f32 v37, v46, v47, 0x4b400000
	v_fmaak_f32 v19, v19, v47, 0x4b400000
	v_perm_b32 v19, v19, v37, s25
	v_perm_b32 v23, v36, v23, s25
	v_perm_b32 v23, v19, v23, s26
	v_lshl_add_u64 v[36:37], v[26:27], 0, s[0:1]
	global_store_dwordx4 v[36:37], v[20:23], off
	s_and_saveexec_b64 s[0:1], s[2:3]
	s_cbranch_execz .LBB0_2075
	s_waitcnt lgkmcnt(0)
	v_add_f32_e32 v17, v17, v18
	v_fmamk_f32 v17, v17, 0x3a800000, v35
	v_mul_f32_e32 v18, 0x4b800000, v17
	v_cmp_gt_f32_e32 vcc, s27, v17
	s_lshl_b64 s[14:15], s[4:5], 2
	s_add_u32 s14, s20, s14
	v_cndmask_b32_e32 v17, v17, v18, vcc
	v_rsq_f32_e32 v17, v17
	v_mul_f32_e32 v16, 0x3c010204, v16
	s_addc_u32 s15, s21, s15
	v_mul_f32_e32 v18, 0x45800000, v17
	v_cndmask_b32_e32 v17, v17, v18, vcc
	v_mul_f32_e32 v16, v16, v17
	global_store_dword v34, v16, s[14:15]
; #define GAS __attribute__((address_space(1)))
; __device__ __forceinline__ void quant_row(const v4u a, const v4u b, unsigned char* dst, float* sc, bool is_w, int lane) {
;     float v[16];
; #pragma unroll
;     for (int i = 0; i < 4; ++i) { v[2 * i] = __uint_as_float(a[i] << 16); v[2 * i + 1] = __uint_as_float(a[i] & 0xffff0000u); v[8 + 2 * i] = __uint_as_float(b[i] << 16); v[8 + 2 * i + 1] = __uint_as_float(b[i] & 0xffff0000u); }
;     float mx = 0.f, ss = 0.f;
; #pragma unroll
;     for (int i = 0; i < 16; ++i) { mx = fmaxf(mx, fabsf(v[i])); ss += v[i] * v[i]; }
;     mx = wave_max(mx); ss = wave_sum(ss);
;     const float inv = mx > 0.f ? 127.f / mx : 0.f;
;     v4u q;
; #pragma unroll
;     for (int w = 0; w < 4; ++w) q[w] = q8x4((f32x4){v[4 * w], v[4 * w + 1], v[4 * w + 2], v[4 * w + 3]}, inv);
;     *(GAS v4u*)(dst + 16 * lane) = q;
;     if (lane == 0) *sc = is_w ? mx * (1.f / 127.f) : rsqrtf(ss * (1.f / DM) + EPS) * (mx * (1.f / 127.f));
; }
; __device__ __forceinline__ void p_quant(Frame& F) {
;     ...
;     for (int r = first; r < last; r += 4 * step) {
;         v4u a[4], b[4];
; #pragma unroll
;         for (int k = 0; k < 4; ++k) {
;             const int rk = r + k * step < last ? r + k * step : r;
;             const bf16* sp = WSP(bf16, WS_H2B) + (size_t)rk * 1024;
;             a[k] = *(const GAS v4u*)(sp + 16 * l); b[k] = *(const GAS v4u*)(sp + 16 * l + 8);
;         }
; #pragma unroll
;         for (int k = 0; k < 4; ++k) {
;             const int rk = r + k * step; if (rk >= last) break;
;             quant_row(a[k], b[k], WSP(unsigned char, WS_A8) + (size_t)rk * 1024, WSP(float, WS_RS8) + rk, false, l);
.LBB0_2075:
	s_or_b64 exec, exec, s[0:1]
	s_andn2_b64 vcc, exec, s[12:13]
	s_cbranch_vccnz .LBB0_2069
	s_waitcnt vmcnt(4)
	v_lshlrev_b32_e32 v16, 16, v12
	v_and_b32_e32 v12, 0xffff0000, v12
	v_lshlrev_b32_e32 v17, 16, v8
	s_waitcnt lgkmcnt(0)
	v_and_b32_e32 v18, 0xffff0000, v8
	v_lshlrev_b32_e32 v19, 16, v13
	v_and_b32_e32 v13, 0xffff0000, v13
	v_max3_f32 v8, |v16|, 0, |v12|
	v_lshlrev_b32_e32 v22, 16, v14
	v_and_b32_e32 v14, 0xffff0000, v14
	v_max3_f32 v8, v8, |v19|, |v13|
	v_lshlrev_b32_e32 v37, 16, v15
	v_and_b32_e32 v15, 0xffff0000, v15
	v_max3_f32 v8, v8, |v22|, |v14|
	v_max3_f32 v8, v8, |v37|, |v15|
	v_lshlrev_b32_e32 v20, 16, v9
	v_and_b32_e32 v21, 0xffff0000, v9
	v_max3_f32 v8, v8, |v17|, |v18|
	v_lshlrev_b32_e32 v23, 16, v10
	v_and_b32_e32 v36, 0xffff0000, v10
	v_max3_f32 v8, v8, |v20|, |v21|
	v_lshlrev_b32_e32 v38, 16, v11
	v_and_b32_e32 v11, 0xffff0000, v11
	v_max3_f32 v8, v8, |v23|, |v36|
	v_max3_f32 v8, v8, |v38|, |v11|
	s_nop 1
	v_mov_b32_dpp v10, v8 quad_perm:[1,0,3,2] row_mask:0xf bank_mask:0xf
	v_mul_f32_e32 v9, v12, v12
	v_fmac_f32_e32 v9, v16, v16
	v_fmac_f32_e32 v9, v19, v19
	v_fmac_f32_e32 v9, v13, v13
	s_waitcnt lgkmcnt(0)
	v_max_f32_e32 v10, v10, v10
	v_max_f32_e32 v8, v8, v10
	v_fmac_f32_e32 v9, v22, v22
	s_nop 1
	v_mov_b32_dpp v10, v8 quad_perm:[2,3,0,1] row_mask:0xf bank_mask:0xf
	v_fmac_f32_e32 v9, v14, v14
	v_fmac_f32_e32 v9, v37, v37
	v_fmac_f32_e32 v9, v15, v15
	v_fmac_f32_e32 v9, v17, v17
	v_fmac_f32_e32 v9, v18, v18
	s_waitcnt lgkmcnt(0)
	v_max_f32_e32 v10, v10, v10
	v_fmac_f32_e32 v9, v20, v20
	v_max_f32_e32 v8, v8, v10
	v_fmac_f32_e32 v9, v21, v21
	s_nop 1
	v_mov_b32_dpp v10, v8 row_half_mirror row_mask:0xf bank_mask:0xf
	v_fmac_f32_e32 v9, v23, v23
	v_fmac_f32_e32 v9, v36, v36
	v_fmac_f32_e32 v9, v38, v38
	v_fmac_f32_e32 v9, v11, v11
	s_waitcnt lgkmcnt(0)
	v_max_f32_e32 v10, v10, v10
	s_nop 1
	v_mov_b32_dpp v39, v9 quad_perm:[1,0,3,2] row_mask:0xf bank_mask:0xf
	v_max_f32_e32 v8, v8, v10
	s_nop 1
	v_mov_b32_dpp v10, v8 row_mirror row_mask:0xf bank_mask:0xf
	s_ashr_i32 s9, s8, 31
	s_waitcnt lgkmcnt(0)
	v_add_f32_e32 v9, v9, v39
	s_nop 1
	v_mov_b32_dpp v39, v9 quad_perm:[2,3,0,1] row_mask:0xf bank_mask:0xf
	s_waitcnt lgkmcnt(0)
	v_max_f32_e32 v10, v10, v10
	v_max_f32_e32 v8, v8, v10
	ds_bpermute_b32 v10, v32, v8
	s_waitcnt lgkmcnt(0)
	v_add_f32_e32 v9, v9, v39
	s_nop 1
	v_mov_b32_dpp v39, v9 row_half_mirror row_mask:0xf bank_mask:0xf
	s_waitcnt lgkmcnt(0)
	v_max_f32_e32 v10, v10, v10
	v_max_f32_e32 v8, v8, v10
	ds_bpermute_b32 v10, v33, v8
	s_waitcnt lgkmcnt(0)
	v_add_f32_e32 v9, v9, v39
	s_nop 1
	v_mov_b32_dpp v39, v9 row_mirror row_mask:0xf bank_mask:0xf
	s_waitcnt lgkmcnt(0)
	v_max_f32_e32 v10, v10, v10
	v_max_f32_e32 v8, v8, v10
	s_waitcnt lgkmcnt(0)
	v_add_f32_e32 v9, v9, v39
	v_div_scale_f32 v39, s[0:1], v8, v8, s24
	v_rcp_f32_e32 v40, v39
	ds_bpermute_b32 v10, v32, v9
	s_lshl_b64 s[0:1], s[8:9], 10
	v_fma_f32 v41, -v39, v40, 1.0
	v_fmac_f32_e32 v40, v41, v40
	v_div_scale_f32 v41, vcc, s24, v8, s24
	v_mul_f32_e32 v42, v41, v40
	v_fma_f32 v43, -v39, v42, v41
	v_fmac_f32_e32 v42, v43, v40
	v_fma_f32 v39, -v39, v42, v41
	v_div_fmas_f32 v39, v39, v40, v42
	v_div_fixup_f32 v39, v39, v8, s24
	v_cmp_lt_f32_e32 vcc, 0, v8
	s_waitcnt lgkmcnt(0)
	v_add_f32_e32 v9, v9, v10
	ds_bpermute_b32 v10, v33, v9
	v_cndmask_b32_e32 v39, 0, v39, vcc
	v_fmaak_f32 v16, v16, v39, 0x4b400000
	v_fmaak_f32 v12, v12, v39, 0x4b400000
	v_fmaak_f32 v19, v19, v39, 0x4b400000
	v_fmaak_f32 v13, v13, v39, 0x4b400000
	v_perm_b32 v13, v13, v19, s25
	v_perm_b32 v12, v12, v16, s25
	v_perm_b32 v12, v13, v12, s26
	v_fmaak_f32 v13, v22, v39, 0x4b400000
	v_fmaak_f32 v14, v14, v39, 0x4b400000
	v_fmaak_f32 v16, v37, v39, 0x4b400000
	v_fmaak_f32 v15, v15, v39, 0x4b400000
	v_perm_b32 v15, v15, v16, s25
	v_perm_b32 v13, v14, v13, s25
	v_perm_b32 v13, v15, v13, s26
	v_fmaak_f32 v14, v17, v39, 0x4b400000
	v_fmaak_f32 v15, v18, v39, 0x4b400000
	v_fmaak_f32 v16, v20, v39, 0x4b400000
	v_fmaak_f32 v17, v21, v39, 0x4b400000
	v_perm_b32 v16, v17, v16, s25
	v_perm_b32 v14, v15, v14, s25
	v_perm_b32 v14, v16, v14, s26
	v_fmaak_f32 v15, v23, v39, 0x4b400000
	v_fmaak_f32 v16, v36, v39, 0x4b400000
	v_fmaak_f32 v17, v38, v39, 0x4b400000
	v_fmaak_f32 v11, v11, v39, 0x4b400000
	v_perm_b32 v11, v11, v17, s25
	v_perm_b32 v15, v16, v15, s25
	v_perm_b32 v15, v11, v15, s26
	v_lshl_add_u64 v[16:17], v[26:27], 0, s[0:1]
	global_store_dwordx4 v[16:17], v[12:15], off
	s_and_saveexec_b64 s[0:1], s[2:3]
	s_cbranch_execz .LBB0_2078
	s_waitcnt lgkmcnt(0)
	v_add_f32_e32 v9, v9, v10
	v_fmamk_f32 v9, v9, 0x3a800000, v35
	v_mul_f32_e32 v10, 0x4b800000, v9
	v_cmp_gt_f32_e32 vcc, s27, v9
	s_lshl_b64 s[8:9], s[8:9], 2
	s_add_u32 s8, s20, s8
	v_cndmask_b32_e32 v9, v9, v10, vcc
	v_rsq_f32_e32 v9, v9
	v_mul_f32_e32 v8, 0x3c010204, v8
	s_addc_u32 s9, s21, s9
	v_mul_f32_e32 v10, 0x45800000, v9
	v_cndmask_b32_e32 v9, v9, v10, vcc
	v_mul_f32_e32 v8, v8, v9
	global_store_dword v34, v8, s[8:9]
; #define GAS __attribute__((address_space(1)))
; __device__ __forceinline__ int lane_now() { int l; asm volatile("v_mbcnt_lo_u32_b32 %0, -1, 0\n\tv_mbcnt_hi_u32_b32 %0, -1, %0" : "=v"(l)); return l; }
; __device__ __forceinline__ void xcd_barrier(const XcdBarrier& b) {
;     asm volatile("s_waitcnt vmcnt(0)" ::: "memory");
;     __syncthreads();
;     if (b.wave == 0 && lane_now() == 0) {
;         unsigned* bar = b.bar;
;         __builtin_amdgcn_s_waitcnt(0);
;         unsigned nloc = b.st[0], nx = b.st[1];
;         if (nloc == 0u) { unsigned mode, xi; xcd_barrier_complete(bar, b.x, nloc, nx, mode, xi); b.st[0] = nloc; b.st[1] = nx; b.st[3] = mode; b.st[4] = xi; }
; __device__ __forceinline__ void quant_row(const v4u a, const v4u b, unsigned char* dst, float* sc, bool is_w, int lane) {
;     float v[16];
; #pragma unroll
;     for (int i = 0; i < 4; ++i) { v[2 * i] = __uint_as_float(a[i] << 16); v[2 * i + 1] = __uint_as_float(a[i] & 0xffff0000u); v[8 + 2 * i] = __uint_as_float(b[i] << 16); v[8 + 2 * i + 1] = __uint_as_float(b[i] & 0xffff0000u); }
;     float mx = 0.f, ss = 0.f;
; #pragma unroll
;     for (int i = 0; i < 16; ++i) { mx = fmaxf(mx, fabsf(v[i])); ss += v[i] * v[i]; }
;     mx = wave_max(mx); ss = wave_sum(ss);
;     const float inv = mx > 0.f ? 127.f / mx : 0.f;
;     v4u q;
; #pragma unroll
;     for (int w = 0; w < 4; ++w) q[w] = q8x4((f32x4){v[4 * w], v[4 * w + 1], v[4 * w + 2], v[4 * w + 3]}, inv);
;     *(GAS v4u*)(dst + 16 * lane) = q;
;     if (lane == 0) *sc = is_w ? mx * (1.f / 127.f) : rsqrtf(ss * (1.f / DM) + EPS) * (mx * (1.f / 127.f));
; }
.LBB0_2078:
	s_or_b64 exec, exec, s[0:1]
	s_andn2_b64 vcc, exec, s[10:11]
	s_cbranch_vccnz .LBB0_2069
	s_waitcnt vmcnt(3)
	v_lshlrev_b32_e32 v8, 16, v4
	v_and_b32_e32 v4, 0xffff0000, v4
	v_lshlrev_b32_e32 v9, 16, v0
	s_waitcnt lgkmcnt(0)
	v_and_b32_e32 v10, 0xffff0000, v0
	v_lshlrev_b32_e32 v11, 16, v5
	v_and_b32_e32 v5, 0xffff0000, v5
	v_max3_f32 v0, |v8|, 0, |v4|
	v_lshlrev_b32_e32 v14, 16, v6
	v_and_b32_e32 v6, 0xffff0000, v6
	v_max3_f32 v0, v0, |v11|, |v5|
	v_lshlrev_b32_e32 v17, 16, v7
	v_and_b32_e32 v7, 0xffff0000, v7
	v_max3_f32 v0, v0, |v14|, |v6|
	v_max3_f32 v0, v0, |v17|, |v7|
	v_lshlrev_b32_e32 v12, 16, v1
	v_and_b32_e32 v13, 0xffff0000, v1
	v_max3_f32 v0, v0, |v9|, |v10|
	v_lshlrev_b32_e32 v15, 16, v2
	v_and_b32_e32 v16, 0xffff0000, v2
	v_max3_f32 v0, v0, |v12|, |v13|
	v_lshlrev_b32_e32 v18, 16, v3
	v_and_b32_e32 v3, 0xffff0000, v3
	v_max3_f32 v0, v0, |v15|, |v16|
	v_max3_f32 v0, v0, |v18|, |v3|
	s_nop 1
	v_mov_b32_dpp v2, v0 quad_perm:[1,0,3,2] row_mask:0xf bank_mask:0xf
	v_mul_f32_e32 v1, v4, v4
	v_fmac_f32_e32 v1, v8, v8
	v_fmac_f32_e32 v1, v11, v11
	v_fmac_f32_e32 v1, v5, v5
	s_waitcnt lgkmcnt(0)
	v_max_f32_e32 v2, v2, v2
	v_max_f32_e32 v0, v0, v2
	v_fmac_f32_e32 v1, v14, v14
	s_nop 1
	v_mov_b32_dpp v2, v0 quad_perm:[2,3,0,1] row_mask:0xf bank_mask:0xf
	v_fmac_f32_e32 v1, v6, v6
	v_fmac_f32_e32 v1, v17, v17
	v_fmac_f32_e32 v1, v7, v7
	v_fmac_f32_e32 v1, v9, v9
	v_fmac_f32_e32 v1, v10, v10
	s_waitcnt lgkmcnt(0)
	v_max_f32_e32 v2, v2, v2
	v_fmac_f32_e32 v1, v12, v12
	v_max_f32_e32 v0, v0, v2
	v_fmac_f32_e32 v1, v13, v13
	s_nop 1
	v_mov_b32_dpp v2, v0 row_half_mirror row_mask:0xf bank_mask:0xf
	v_fmac_f32_e32 v1, v15, v15
	v_fmac_f32_e32 v1, v16, v16
	v_fmac_f32_e32 v1, v18, v18
	v_fmac_f32_e32 v1, v3, v3
	s_waitcnt lgkmcnt(0)
	v_max_f32_e32 v2, v2, v2
	s_nop 1
	v_mov_b32_dpp v19, v1 quad_perm:[1,0,3,2] row_mask:0xf bank_mask:0xf
	v_max_f32_e32 v0, v0, v2
	s_nop 1
	v_mov_b32_dpp v2, v0 row_mirror row_mask:0xf bank_mask:0xf
	s_ashr_i32 s7, s6, 31
	s_waitcnt lgkmcnt(0)
	v_add_f32_e32 v1, v1, v19
	s_nop 1
	v_mov_b32_dpp v19, v1 quad_perm:[2,3,0,1] row_mask:0xf bank_mask:0xf
	s_waitcnt lgkmcnt(0)
	v_max_f32_e32 v2, v2, v2
	v_max_f32_e32 v0, v0, v2
	ds_bpermute_b32 v2, v32, v0
	s_waitcnt lgkmcnt(0)
	v_add_f32_e32 v1, v1, v19
	s_nop 1
	v_mov_b32_dpp v19, v1 row_half_mirror row_mask:0xf bank_mask:0xf
	s_waitcnt lgkmcnt(0)
	v_max_f32_e32 v2, v2, v2
	v_max_f32_e32 v0, v0, v2
	ds_bpermute_b32 v2, v33, v0
	s_waitcnt lgkmcnt(0)
	v_add_f32_e32 v1, v1, v19
	s_nop 1
	v_mov_b32_dpp v19, v1 row_mirror row_mask:0xf bank_mask:0xf
	s_waitcnt lgkmcnt(0)
	v_max_f32_e32 v2, v2, v2
	v_max_f32_e32 v0, v0, v2
	s_waitcnt lgkmcnt(0)
	v_add_f32_e32 v1, v1, v19
	v_div_scale_f32 v19, s[0:1], v0, v0, s24
	v_rcp_f32_e32 v20, v19
	ds_bpermute_b32 v2, v32, v1
	s_lshl_b64 s[0:1], s[6:7], 10
	v_fma_f32 v21, -v19, v20, 1.0
	v_fmac_f32_e32 v20, v21, v20
	v_div_scale_f32 v21, vcc, s24, v0, s24
	v_mul_f32_e32 v22, v21, v20
	v_fma_f32 v23, -v19, v22, v21
	v_fmac_f32_e32 v22, v23, v20
	v_fma_f32 v19, -v19, v22, v21
	v_div_fmas_f32 v19, v19, v20, v22
	v_div_fixup_f32 v19, v19, v0, s24
	v_cmp_lt_f32_e32 vcc, 0, v0
	s_waitcnt lgkmcnt(0)
	v_add_f32_e32 v1, v1, v2
	ds_bpermute_b32 v2, v33, v1
	v_cndmask_b32_e32 v19, 0, v19, vcc
	v_fmaak_f32 v8, v8, v19, 0x4b400000
	v_fmaak_f32 v4, v4, v19, 0x4b400000
	v_fmaak_f32 v11, v11, v19, 0x4b400000
	v_fmaak_f32 v5, v5, v19, 0x4b400000
	v_perm_b32 v5, v5, v11, s25
	v_perm_b32 v4, v4, v8, s25
	v_perm_b32 v4, v5, v4, s26
	v_fmaak_f32 v5, v14, v19, 0x4b400000
	v_fmaak_f32 v6, v6, v19, 0x4b400000
	v_fmaak_f32 v8, v17, v19, 0x4b400000
	v_fmaak_f32 v7, v7, v19, 0x4b400000
	v_perm_b32 v7, v7, v8, s25
	v_perm_b32 v5, v6, v5, s25
	v_perm_b32 v5, v7, v5, s26
	v_fmaak_f32 v6, v9, v19, 0x4b400000
	v_fmaak_f32 v7, v10, v19, 0x4b400000
	v_fmaak_f32 v8, v12, v19, 0x4b400000
	v_fmaak_f32 v9, v13, v19, 0x4b400000
	v_perm_b32 v8, v9, v8, s25
	v_perm_b32 v6, v7, v6, s25
	v_perm_b32 v6, v8, v6, s26
	v_fmaak_f32 v7, v15, v19, 0x4b400000
	v_fmaak_f32 v8, v16, v19, 0x4b400000
	v_fmaak_f32 v9, v18, v19, 0x4b400000
	v_fmaak_f32 v3, v3, v19, 0x4b400000
	v_perm_b32 v3, v3, v9, s25
	v_perm_b32 v7, v8, v7, s25
	v_perm_b32 v7, v3, v7, s26
	v_lshl_add_u64 v[8:9], v[26:27], 0, s[0:1]
	global_store_dwordx4 v[8:9], v[4:7], off
	s_and_saveexec_b64 s[0:1], s[2:3]
	s_cbranch_execz .LBB0_2068
	s_waitcnt lgkmcnt(0)
	v_add_f32_e32 v1, v1, v2
	v_fmamk_f32 v1, v1, 0x3a800000, v35
	v_mul_f32_e32 v2, 0x4b800000, v1
	v_cmp_gt_f32_e32 vcc, s27, v1
	s_lshl_b64 s[6:7], s[6:7], 2
	s_add_u32 s6, s20, s6
	v_cndmask_b32_e32 v1, v1, v2, vcc
	v_rsq_f32_e32 v1, v1
	v_mul_f32_e32 v0, 0x3c010204, v0
	s_addc_u32 s7, s21, s7
	v_mul_f32_e32 v2, 0x45800000, v1
	v_cndmask_b32_e32 v1, v1, v2, vcc
	v_mul_f32_e32 v0, v0, v1
	global_store_dword v34, v0, s[6:7]
	s_branch .LBB0_2068
.LBB0_2081:
	s_cmp_lt_i32 s95, 12
	s_cbranch_scc1 .LBB0_2132
	s_waitcnt vmcnt(0)
	v_readlane_b32 s0, v254, 0
	s_cmp_gt_u32 s0, 63
	s_waitcnt lgkmcnt(0)
	s_barrier
	s_cbranch_scc1 .LBB0_2131
	s_waitcnt vmcnt(2)
	v_mbcnt_lo_u32_b32 v0, -1, 0
	v_mbcnt_hi_u32_b32 v0, -1, v0
	s_nop 0
	v_cmp_eq_u32_e32 vcc, 0, v0
	s_and_saveexec_b64 s[38:39], vcc
	s_cbranch_execz .LBB0_2130
	v_readlane_b32 s0, v254, 8
	s_waitcnt vmcnt(0) expcnt(0) lgkmcnt(0)
	s_nop 0
	v_mov_b32_e32 v0, s0
	ds_read_b32 v2, v0
	ds_read_b32 v0, v0 offset:4
	s_waitcnt lgkmcnt(0)
	v_cmp_ne_u32_e32 vcc, 0, v2
	s_cbranch_vccnz .LBB0_2098
	v_readlane_b32 s2, v254, 3
	v_readlane_b32 s3, v254, 4
	s_load_dwordx2 s[0:1], s[2:3], 0x4
	s_add_u32 s2, s42, 0x4200
	s_addc_u32 s3, s43, 0
	s_add_u32 s4, s42, 0x4400
	s_addc_u32 s5, s43, 0
	s_add_u32 s6, s42, 0x4500
	s_addc_u32 s7, s43, 0
	s_add_u32 s8, s42, 0x4600
	s_addc_u32 s9, s43, 0
	s_add_u32 s10, s42, 0x4700
	s_addc_u32 s11, s43, 0
	s_add_u32 s12, s42, 0x4800
	s_addc_u32 s13, s43, 0
	s_add_u32 s14, s42, 0x4900
	s_addc_u32 s15, s43, 0
	s_add_u32 s16, s42, 0x4a00
	s_addc_u32 s17, s43, 0
	s_add_u32 s18, s42, 0x4b00
	s_addc_u32 s19, s43, 0
	s_add_u32 s20, s42, 0x4c00
	s_addc_u32 s21, s43, 0
	s_add_u32 s22, s42, 0x4d00
	s_addc_u32 s23, s43, 0
	s_add_u32 s24, s42, 0x4e00
	s_addc_u32 s25, s43, 0
	s_add_u32 s26, s42, 0x4f00
	s_addc_u32 s27, s43, 0
	s_add_u32 s28, s42, 0x5000
	s_addc_u32 s29, s43, 0
	s_add_u32 s30, s42, 0x5100
	s_addc_u32 s31, s43, 0
	s_add_u32 s34, s42, 0x5200
	s_addc_u32 s35, s43, 0
	s_waitcnt lgkmcnt(0)
	s_mul_i32 s52, s0, s33
	s_add_u32 s36, s42, 0x5300
	s_mul_i32 s52, s52, s1
	s_addc_u32 s37, s43, 0
	s_mov_b32 s53, 1
	v_mov_b32_e32 v16, 0
	s_branch .LBB0_2087
